# mixing phases: work-queue atomic return deferred to item end (dedicated VGPR), conservative vmcnt(0) waits inside mLSTM item load sections replaced by counted waits
# speedup vs baseline: 1.0060x; 1.0060x over previous
.LBB0_451:
	s_mov_b64 s[14:15], exec
	v_mbcnt_lo_u32_b32 v8, s14, 0
	v_mbcnt_hi_u32_b32 v8, s15, v8
	v_cmp_eq_u32_e32 vcc, 0, v8
	s_and_saveexec_b64 s[12:13], vcc
	s_cbranch_execz .LBB0_453
	s_bcnt1_i32_b64 s14, s[14:15]
	v_mov_b32_e32 v9, s14
	v_readlane_b32 s14, v254, 43
	v_readlane_b32 s15, v254, 44
	s_nop 4
	global_atomic_add v248, v181, v9, s[14:15] sc0
.LBB0_453:
	s_or_b64 exec, exec, s[12:13]
	s_or_b64 exec, exec, s[8:9]
	s_cmp_ge_i32 s65, s44
	s_mov_b64 s[8:9], -1
	s_cbranch_scc0 .LBB0_450

.LBB0_514:
	s_or_b64 exec, exec, s[12:13]
	v_add_u32_e32 v8, s9, v142
	v_cmp_lt_i32_e64 s[14:15], -1, v8
	v_mov_b32_e32 v28, 0
	v_mov_b32_e32 v32, 0
	v_mov_b32_e32 v33, 0
	v_mov_b32_e32 v34, 0
	v_mov_b32_e32 v35, 0
	s_and_saveexec_b64 s[12:13], s[14:15]
	s_cbranch_execz .LBB0_516
	v_mov_b32_e32 v9, v181
	v_lshl_add_u64 v[14:15], s[52:53], 0, v[8:9]
	s_movk_i32 s27, 0x1c00
	v_mad_u64_u32 v[16:17], s[40:41], v14, s27, v[68:69]
	v_mad_i32_i24 v17, v15, s27, v17
	global_load_dwordx4 v[32:35], v[16:17], off offset:3072
.LBB0_516:
	s_or_b64 exec, exec, s[12:13]
	v_add_u32_e32 v70, 4, v180
	v_cmp_lt_i32_e64 s[12:13], -5, v180
	v_mov_b32_e32 v29, 0
	v_mov_b32_e32 v30, 0
	v_mov_b32_e32 v31, 0
	s_and_saveexec_b64 s[54:55], s[12:13]
	s_cbranch_execz .LBB0_518
	v_mov_b32_e32 v71, v181
	v_lshl_add_u64 v[14:15], s[52:53], 0, v[70:71]
	s_movk_i32 s27, 0x1c00
	v_mad_u64_u32 v[16:17], s[40:41], v14, s27, v[68:69]
	v_mad_i32_i24 v17, v15, s27, v17
	global_load_dwordx4 v[28:31], v[16:17], off offset:3072
.LBB0_518:
	s_or_b64 exec, exec, s[54:55]
	v_mov_b32_e32 v20, 0
	v_mov_b32_e32 v24, 0
	v_mov_b32_e32 v25, 0
	v_mov_b32_e32 v26, 0
	v_mov_b32_e32 v27, 0
	s_and_saveexec_b64 s[54:55], vcc
	s_cbranch_execz .LBB0_520
	v_lshl_add_u64 v[14:15], s[52:53], 0, v[180:181]
	s_movk_i32 s27, 0x1c00
	v_mad_u64_u32 v[16:17], s[40:41], v14, s27, v[68:69]
	v_mad_i32_i24 v9, v15, s27, v17
	v_add_co_u32_e32 v14, vcc, 0x1000, v16
	s_nop 1
	v_addc_co_u32_e32 v15, vcc, 0, v9, vcc
	global_load_dwordx4 v[24:27], v[14:15], off

.LBB0_530:
	s_waitcnt vmcnt(16)
	ds_write2st64_b32 v144, v79, v80 offset1:8
	s_and_saveexec_b64 s[14:15], s[58:59]
	ds_write_b32 v144, v78 offset:4096
	s_or_b64 exec, exec, s[14:15]
	s_waitcnt lgkmcnt(0)
	s_barrier
	s_mov_b64 s[14:15], exec
	v_readlane_b32 s16, v254, 55
	v_readlane_b32 s17, v254, 56
	s_and_b64 s[16:17], s[14:15], s[16:17]
	s_mov_b64 exec, s[16:17]
	s_cbranch_execz .LBB0_534
	v_mov_b32_e32 v78, 0x3f803f80
	s_nop 0
	v_mov_b32_e32 v79, v78
	v_mov_b32_e32 v80, v78
	v_mov_b32_e32 v81, v78
	ds_write_b128 v145, v[78:81] offset:35072

.LBB0_549:
	s_and_b64 vcc, exec, s[12:13]
	s_cbranch_vccz .LBB0_571
	s_lshl_b32 s16, s25, 7
	v_or_b32_e32 v8, s16, v138
	v_add_u32_e32 v8, v8, v139
	v_ashrrev_i32_e32 v9, 31, v8
	v_lshl_add_u64 v[10:11], v[8:9], 2, s[36:37]
	v_add_u32_e32 v8, 0x200, v8
	v_ashrrev_i32_e32 v9, 31, v8
	v_lshl_add_u64 v[8:9], v[8:9], 2, s[36:37]
	global_load_dword v37, v[10:11], off
	global_load_dword v40, v[8:9], off
	v_or_b32_e32 v8, s16, v141
	v_lshlrev_b32_e32 v8, 2, v8
	global_load_dword v36, v8, s[88:89]
	s_lshl_b32 s9, s65, 6
	s_and_b32 s9, s9, 0x7c0
	s_ashr_i32 s27, s26, 31
	v_add_u32_e32 v180, s9, v160
	s_lshl_b32 s90, s25, 8
	s_lshl_b64 s[12:13], s[26:27], 11
	v_lshl_add_u64 v[28:29], v[118:119], 0, s[90:91]
	v_cmp_lt_i32_e32 vcc, -1, v180
	v_mov_b32_e32 v20, 0
	v_mov_b32_e32 v24, 0
	v_mov_b32_e32 v25, 0
	v_mov_b32_e32 v26, 0
	v_mov_b32_e32 v27, 0
	s_and_saveexec_b64 s[14:15], vcc
	s_cbranch_execz .LBB0_552
	v_lshl_add_u64 v[8:9], s[12:13], 0, v[180:181]
	s_movk_i32 s17, 0x1c00
	v_mad_u64_u32 v[10:11], s[18:19], v8, s17, v[28:29]
	v_mad_i32_i24 v9, v9, s17, v11
	v_add_co_u32_e32 v8, vcc, 0x1000, v10
	s_nop 1
	v_addc_co_u32_e32 v9, vcc, 0, v9, vcc
	global_load_dwordx4 v[24:27], v[8:9], off

.LBB0_562:
	s_waitcnt vmcnt(7)
	ds_write2st64_b32 v144, v37, v40 offset1:8
	s_and_saveexec_b64 s[14:15], s[58:59]
	ds_write_b32 v144, v36 offset:4096
	s_or_b64 exec, exec, s[14:15]
	s_waitcnt lgkmcnt(0)
	s_barrier
	s_mov_b64 s[14:15], exec
	v_readlane_b32 s16, v254, 55
	v_readlane_b32 s17, v254, 56
	s_and_b64 s[16:17], s[14:15], s[16:17]
	s_mov_b64 exec, s[16:17]
	s_cbranch_execz .LBB0_566
	v_mov_b32_e32 v40, 0x3f803f80
	s_nop 0
	v_mov_b32_e32 v41, v40
	v_mov_b32_e32 v42, v40
	v_mov_b32_e32 v43, v40
	ds_write_b128 v145, v[40:43] offset:35072

.LBB0_571:
	s_and_saveexec_b64 s[8:9], s[46:47]
	s_cbranch_execz .LBB0_447
	v_readlane_b32 s12, v254, 20
	s_waitcnt vmcnt(0)
	s_nop 0
	v_mov_b32_e32 v8, s12
	ds_write_b32 v8, v248
	s_branch .LBB0_447
